# one static s_setprio 1 at kernel entry for waves 0-3 (the leading half of every GEMM K-loop)
# baseline (speedup 1.0000x reference)
; #define LAS __attribute__((address_space(3)))
; #define KARG ((const __attribute__((address_space(4))) Args*)__builtin_amdgcn_kernarg_segment_ptr())
; #define STAMP(i) do { if (F.bid == PROBE_BID && F.tid == 0 && ((i) == PROBE_A || (i) == PROBE_B)) { const unsigned long long t_ = __builtin_amdgcn_s_memrealtime(); volatile LAS unsigned* m_ = (volatile LAS unsigned*)(F.lds + MISC_OFF) + ((i) == PROBE_A ? 16 : 18); m_[0] = (unsigned)t_; m_[1] = (unsigned)(t_ >> 32); } } while (0)
; #define STAMP(i) do { } while (0)
; #define SEAM(k) do { if (IN(k) && IN((k) + 1)) { XcdBarrier b_; b_.bar = (unsigned*)(P_ctl + CW_BAR); b_.x = xb_xcc_id(); b_.st = MISC + 8; xcd_barrier(b_); } } while (0)
; __global__ void __launch_bounds__(NWAVES * 64, 2) hymba_fwd(Args args) {
;     ...
;     Frame F; F.lds = (LAS unsigned char*)lds_raw; F.tid = threadIdx.x; F.lane = F.tid & 63; F.wave = __builtin_amdgcn_readfirstlane(F.tid >> 6); F.G = KARG->grid; F.bid = blockIdx.x;
;     volatile LAS unsigned* MISC = (volatile LAS unsigned*)(F.lds + MISC_OFF);
;     Ptrs P;
;     for (int u = F.tid; u < (LDS_BYTES - LDSCTL_OFF) / 4; u += NWAVES * 64) ((LAS unsigned*)(F.lds + LDSCTL_OFF))[u] = 0u;
;     __syncthreads();
;     if (N_LAUNCHES == 1) (void)xcd_barrier_post((unsigned*)(P_ctl + CW_BAR), MISC + 8);
;     const int lo = KARG->ph_lo, hi = KARG->ph_hi;
;     STAMP(0);
;     ...
;     if (IN(0)) { for (int rep = 0; rep < NREP_P0; ++rep) p0_prologue(F, P); } SEAM(0); STAMP(1);
.LBB0_5:
	s_or_b64 exec, exec, s[4:5]
	s_load_dwordx2 s[6:7], s[0:1], 0xe0
	s_lshr_b32 s94, s60, 6
	s_cmp_gt_u32 s94, 3
	s_cbranch_scc1 .Lprio_skip
	s_setprio 1
